# attention: first unit per workgroup assigned statically by blockIdx%8 so same-head units share an XCD L2; dynamic queue starts at rank 256
# speedup vs baseline: 1.0046x; 1.0036x over previous
; #define LAS __attribute__((address_space(3)))
; template <int VARI>
; __device__ __forceinline__ void attention_phase(ArgsP a, int l, LAS unsigned char* lds, int cslot) {
;     unsigned char* ws = a->ws;
;     const bf16_t* PROJ = (const bf16_t*)(ws + WS_PROJ); const bf16_t* QC = (const bf16_t*)(ws + WS_QC); const bf16_t* KVC = (const bf16_t*)(ws + WS_KVC);
;     bf16_t* MIX = (bf16_t*)(ws + (VARI == 0 ? WS_MIX : WS_END));
;     const int* table = (const int*)(ws + WS_TABLE); int* counter = (int*)(ws + WS_CNT) + 4 * (l + cslot);
;     LAS int* slot = (LAS int*)(lds + LDS_BYTES - 64);
;     const float lam = ((const float*)(ws + WS_LAM))[l], fox_u = ((const float*)(ws + WS_LAM))[8 + l], ub_a = ((const float*)(ws + WS_LAM))[12 + l], ub_c = ((const float*)(ws + WS_LAM))[16 + l];
;     const float linit = 0.8f - 0.6f * expf(-0.3f * (float)l);
;     int tid_ = threadIdx.x; asm volatile("" : "+v"(tid_)); const int tid = tid_;
.LBB0_560:
	s_and_b64 vcc, exec, s[4:5]
	s_cbranch_vccz .LBB0_1343
	s_add_u32 s62, s66, 0x1000
	s_addc_u32 s63, s67, 0
	s_cmpk_eq_i32 s22, 0x100
	s_cselect_b32 s100, 1, 0
	s_lshl_b32 s101, s100, 8
	s_lshl_b32 s4, s64, 2
	s_ashr_i32 s5, s4, 31
	s_lshl_b64 s[4:5], s[4:5], 2
	v_writelane_b32 v255, s6, 13
	s_add_u32 s6, s66, s4
	s_addc_u32 s7, s67, s5
	s_ashr_i32 s65, s64, 31
	s_mul_i32 s4, s64, -12
	s_mul_hi_i32 s2, s64, -12
	s_add_u32 s4, s6, s4
	v_writelane_b32 v255, s6, 14
	s_addc_u32 s5, s7, s2
	global_load_dword v210, v1, s[4:5] offset:128
	global_load_dword v0, v1, s[4:5] offset:160
	global_load_dword v2, v1, s[4:5] offset:176
	s_waitcnt lgkmcnt(0)
	global_load_dword v3, v1, s[4:5] offset:192
	v_cvt_f32_i32_e32 v4, s64
	s_mov_b32 s2, 0x3fb8aa3b
	s_add_u32 s72, s66, 0x14002400
	s_addc_u32 s73, s67, 0
	v_mul_f32_e32 v4, 0xbe99999a, v4
	v_mul_f32_e32 v5, 0x3fb8aa3b, v4
	v_fma_f32 v6, v4, s2, -v5
	v_rndne_f32_e32 v7, v5
	v_fmac_f32_e32 v6, 0x32a5705f, v4
	v_sub_f32_e32 v5, v5, v7
	v_add_f32_e32 v5, v5, v6
	v_exp_f32_e32 v5, v5
	v_cvt_i32_f32_e32 v6, v7
	s_mov_b32 s2, 0xc2ce8ed0
	v_writelane_b32 v255, s7, 15
	v_cmp_ngt_f32_e32 vcc, s2, v4
	v_ldexp_f32 v5, v5, v6
	s_mov_b32 s2, 0x42b17218
	s_add_u32 s6, s66, 0x12000a00
	v_cndmask_b32_e32 v5, 0, v5, vcc
	v_cmp_nlt_f32_e32 vcc, s2, v4
	s_addc_u32 s2, s67, 0
	v_writelane_b32 v255, s2, 16
	s_mov_b32 s2, 0x42700000
	s_add_u32 s7, s66, 0x14000c00
	v_cndmask_b32_e32 v4, v218, v5, vcc
	v_mov_b32_e32 v205, v196
	s_mov_b32 s68, s85
	v_cmp_eq_u32_e64 s[4:5], 0, v205
	s_mov_b32 s85, s6
	s_waitcnt vmcnt(0)
	v_mov_b32_e32 v211, v210
	v_fmaak_f32 v228, 2.0, v0, 0x43160000
	v_cmp_ngt_f32_e64 s[8:9], s2, v3
	s_nop 1
	v_writelane_b32 v255, s8, 17
	s_nop 1
	v_writelane_b32 v255, s9, 18
	v_writelane_b32 v255, s7, 19
	s_addc_u32 s7, s67, 0
	v_writelane_b32 v255, s7, 20
	s_add_u32 s7, s66, 0x14001200
	v_writelane_b32 v255, s7, 21
	s_addc_u32 s7, s67, 0
	v_writelane_b32 v255, s7, 22
	s_add_u32 s7, s66, 0x14001800
	v_writelane_b32 v255, s7, 23
	s_addc_u32 s7, s67, 0
	v_writelane_b32 v255, s7, 24
	s_add_u32 s7, s66, 0x80000
	v_writelane_b32 v255, s7, 25
	s_addc_u32 s7, s67, 0
	v_writelane_b32 v255, s7, 26
	s_add_u32 s7, s66, 0x12000400
	v_writelane_b32 v255, s7, 27
	s_addc_u32 s7, s67, 0
	v_writelane_b32 v255, s7, 28
	v_cmp_ngt_f32_e64 s[8:9], s2, v0
	s_add_u32 s7, s66, 0x14000400
	v_mov_b32_e32 v0, 0xbf4ccccd
	v_writelane_b32 v255, s8, 29
	v_fmamk_f32 v0, v4, 0x3f19999a, v0
	v_add_f32_e32 v229, 1.0, v0
	v_writelane_b32 v255, s9, 30
	v_writelane_b32 v255, s7, 31
	s_addc_u32 s7, s67, 0
	v_writelane_b32 v255, s7, 32
	s_add_u32 s7, s66, 0x14000800
	v_writelane_b32 v255, s7, 33
	s_addc_u32 s7, s67, 0
	v_writelane_b32 v255, s7, 34
	s_lshl_b32 s12, s64, 7
	v_cmp_ngt_f32_e64 s[8:9], s2, v2
	s_ashr_i32 s13, s12, 31
	s_nop 0
	v_writelane_b32 v255, s8, 35
	s_nop 1
	v_writelane_b32 v255, s9, 36
	s_lshl_b64 s[8:9], s[12:13], 2
	v_writelane_b32 v255, s8, 37
	s_nop 1
	v_writelane_b32 v255, s9, 38
	v_writelane_b32 v255, s62, 39
	s_nop 1
	v_writelane_b32 v255, s63, 40
	s_branch .LBB0_566

; template <int VARI>
; __device__ __forceinline__ void attention_phase(ArgsP a, int l, LAS unsigned char* lds, int cslot) {
;     ...
;     for (;;) {
;         if (tid == 0) *slot = atomicAdd(counter, 1);
;         __syncthreads();
;         const int idx = *slot;
;         __syncthreads();
;         if (idx >= NUNITS) break;
;         const int id = table[idx];
.LBB0_566:
	s_cmp_eq_u32 s100, 0
	s_cbranch_scc1 .Ldyn_fetch
	s_mov_b32 s100, 0
	v_readlane_b32 s6, v254, 6
	s_nop 3
	s_and_b32 s2, s6, 7
	s_lshl_b32 s2, s2, 5
	s_lshr_b32 s10, s6, 3
	s_add_i32 s2, s2, s10
	s_cmpk_lt_u32 s2, 0x7e
	s_cbranch_scc0 .Lst_notmla
	s_mul_i32 s10, s2, 0xc31
	s_lshr_b32 s10, s10, 16
	s_mul_i32 s11, s10, 21
	s_sub_i32 s11, s2, s11
	s_lshl_b32 s10, s10, 5
	s_addk_i32 s10, 0x1df
	s_sub_i32 s10, s10, s11
	s_branch .Lst_done
.Lst_notmla:
	s_cmpk_lt_u32 s2, 0xe8
	s_cbranch_scc0 .Lst_fox
	s_add_i32 s6, s2, 0xffffff82
	s_cmpk_ge_u32 s6, 27
	s_cselect_b32 s10, 1, 0
	s_cselect_b32 s11, 27, 0
	s_cmpk_ge_u32 s6, 54
	s_cselect_b32 s10, 2, s10
	s_cselect_b32 s11, 54, s11
	s_cmpk_ge_u32 s6, 0x50
	s_cselect_b32 s10, 3, s10
	s_cselect_b32 s11, 0x50, s11
	s_sub_i32 s6, s6, s11
	s_lshl_b32 s10, s10, 6
	s_add_i32 s10, s10, 63
	s_sub_i32 s10, s10, s6
	s_branch .Lst_done
.Lst_fox:
	s_add_i32 s6, s2, 0xffffff18
	s_lshr_b32 s10, s6, 2
	s_and_b32 s11, s6, 3
	s_lshl_b32 s10, s10, 5
	s_addk_i32 s10, 0x11f
	s_sub_i32 s10, s10, s11
.Lst_done:
	v_mov_b32_e32 v0, s10
	s_mov_b64 s[12:13], -1
	s_branch .Lafter_table

; template <int VARI>
; __device__ __forceinline__ void attention_phase(ArgsP a, int l, LAS unsigned char* lds, int cslot) {
;     ...
;         if (tid == 0) *slot = atomicAdd(counter, 1);
;         __syncthreads();
;         const int idx = *slot;
.LBB0_569:
	s_or_b64 exec, exec, s[14:15]
	s_waitcnt vmcnt(0)
	v_readfirstlane_b32 s2, v2
	v_mov_b32_e32 v2, s88
	s_nop 0
	v_add_u32_e32 v0, s2, v0
	v_add_u32_e32 v0, s101, v0
	ds_write_b32 v2, v0

; template <int MODE, int VARI>
; __device__ __forceinline__ void attn_unit(LAS unsigned char* lds, const int tid, const AttnP& a, float c2, float lam, const float* subln, float outscale, float fox_u, const bool fast) {
;     ...
;       unsigned voff[2], koff[KW / 64], kstp[KW / 64], boff = 0; int vt = t_lo, kt = t_lo;
;       { int tt_ = tid; asm volatile("" : "+v"(tt_)); const int ln_ = tt_ & 63;
; #pragma unroll
;         for (int i_ = 0; i_ < 2; ++i_) { const int ch_ = wid + 8 * i_, b_ = ch_ * 1024 + ln_ * 16, sub_ = b_ >> 9, wi_ = (b_ & 511) >> 1;
; template <int VARI>
; __device__ __forceinline__ void attention_phase(ArgsP a, int l, LAS unsigned char* lds, int cslot) {
;     ...
;         if (id < 256 && (ATM & 1) && (VARI == 0 || (VARI & 1))) {
;             const int h = id >> 6, qb = id & 63;
;             p.Q = PROJ + C_DQ + h * 128; p.qpitch = NINP; p.K0 = PROJ + C_DK + h * 128; p.k0pitch = NINP; p.K1 = p.K0; p.k1pitch = NINP;
;             p.V = PROJ + C_DV + h * 128; p.vpitch = NINP; p.cum = nullptr; p.O = MIX + h * 128; p.P0 = qb * 128; p.rows = 128;
;             attn_unit<0, VARI>(lds, tu, p, 0.125f * LOG2E, lam, a->in[I_SUBLN] + l * 128, 1.0f - linit, 0.f, ub_a < 60.f);
;         } else if (id >= 256 && id < NU_B && (ATM & 2) && (VARI == 0 || (VARI & 2))) {
;             const int h = (id - 256) / QB_PER_HEAD, qb = (id - 256) % QB_PER_HEAD;
;             p.Q = PROJ + C_FQ + h * 128; p.qpitch = NINP; p.K0 = PROJ + C_FK + h * 128; p.k0pitch = NINP; p.K1 = p.K0; p.k1pitch = NINP;
;             p.V = PROJ + C_FV + h * 128; p.vpitch = NINP; p.cum = (const float*)(ws + WS_CUM) + h; p.O = MIX + 512 + h * 128; p.P0 = qb * UNIT_ROWS; p.rows = UNIT_ROWS;
;             attn_unit<1, VARI>(lds, tu, p, 0.08838834764831845f * LOG2E, 0.f, nullptr, 1.f, fox_u, fox_u < 60.f);
;         } else if (id >= NU_B && (ATM & 4) && (VARI == 0 || (VARI & 4))) {
;             const int h = (id - NU_B) / QB_PER_HEAD, qb = (id - NU_B) % QB_PER_HEAD;
;             p.Q = QC + h * 192; p.qpitch = NQUPP; p.K0 = PROJ + C_KR; p.k0pitch = NINP; p.K1 = KVC + h * 256; p.k1pitch = NKVUP;
;             p.V = KVC + h * 256 + 128; p.vpitch = NKVUP; p.cum = nullptr; p.O = MIX + 1280 + h * 128; p.P0 = qb * UNIT_ROWS; p.rows = UNIT_ROWS;
;             attn_unit<2, VARI>(lds, tu, p, 0.07216878364870322f * LOG2E, 0.f, nullptr, 1.f, 0.f, ub_c < 60.f);
.Lafter_table:
	s_movk_i32 s2, 0xff
	v_mov_b32_e32 v230, v205
	s_waitcnt vmcnt(0)
	v_cmp_lt_i32_e32 vcc, s2, v0
	v_readfirstlane_b32 s10, v0
	s_cbranch_vccz .LBB0_802
	s_cmpk_gt_u32 s10, 0x1bf
	s_cbranch_scc0 .LBB0_766
	s_add_i32 s2, s10, 0xfffffe40
	s_lshr_b32 s11, s2, 5
	s_mul_i32 s36, s11, 0xc0
	s_lshl_b64 s[6:7], s[36:37], 1
	s_add_u32 s12, s52, s6
	s_addc_u32 s13, s53, s7
	s_lshl_b32 s2, s11, 9
	v_readlane_b32 s6, v255, 7
	v_readlane_b32 s7, v255, 8
	s_add_u32 s60, s6, s2
	s_addc_u32 s61, s7, 0
	s_lshl_b32 s2, s10, 8
	s_and_b32 s7, s2, 0x1f00
	v_readfirstlane_b32 s2, v230
	s_ashr_i32 s8, s2, 6
	s_lshl_b32 s6, s8, 5
	v_and_b32_e32 v231, 31, v230
	s_add_i32 s76, s6, s7
	v_bfe_u32 v232, v230, 5, 1
	v_or_b32_e32 v0, s76, v231
	v_mov_b64_e32 v[2:3], s[12:13]
	v_mad_i64_i32 v[2:3], s[12:13], v0, s3, v[2:3]
	v_lshlrev_b32_e32 v212, 4, v232
	v_mov_b32_e32 v213, v1
	v_lshl_add_u64 v[2:3], v[2:3], 0, v[212:213]
	global_load_dwordx4 v[144:147], v[2:3], off
	global_load_dwordx4 v[148:151], v[2:3], off offset:32
	global_load_dwordx4 v[152:155], v[2:3], off offset:64
	global_load_dwordx4 v[156:159], v[2:3], off offset:96
	global_load_dwordx4 v[160:163], v[2:3], off offset:128
	global_load_dwordx4 v[164:167], v[2:3], off offset:160
	global_load_dwordx4 v[168:171], v[2:3], off offset:192
	global_load_dwordx4 v[172:175], v[2:3], off offset:224
	global_load_dwordx4 v[176:179], v[2:3], off offset:256
	global_load_dwordx4 v[180:183], v[2:3], off offset:288
	global_load_dwordx4 v[184:187], v[2:3], off offset:320
	global_load_dwordx4 v[188:191], v[2:3], off offset:352
	s_and_b32 s2, s2, 0x3fffffc0
	s_lshl_b32 s2, s2, 2
	v_readlane_b32 s14, v255, 17
	s_add_i32 s9, s7, 0x100
	s_add_i32 s26, s2, 0x100
	v_readlane_b32 s15, v255, 18
	v_and_b32_e32 v213, 63, v230
	s_add_i32 s26, s26, 0x1f800
	s_lshr_b32 s59, s9, 6
	s_mov_b64 s[12:13], -1
	s_and_b64 vcc, exec, s[14:15]
	s_cbranch_vccz .LBB0_609
	s_lshl_b32 s18, s8, 10
	v_mov_b32_e32 v6, v213
	v_mov_b32_e32 v0, v230
	s_ashr_i32 s2, s18, 8
	s_and_b32 s14, s2, -16
	v_lshlrev_b32_e32 v2, 4, v0
	s_lshr_b32 s2, s2, 1
	v_and_b32_e32 v2, 0x200, v2
	v_lshlrev_b32_e32 v3, 3, v0
	v_bfe_u32 v4, v0, 2, 2
	v_lshrrev_b32_e32 v0, 1, v0
	s_and_b32 s15, s2, 4
	v_or_b32_e32 v2, s18, v2
	v_and_or_b32 v4, v0, 8, v4
	s_or_b32 s2, s15, s14
	v_lshrrev_b32_e32 v2, 4, v2
	v_and_b32_e32 v3, 24, v3
	v_or_b32_e32 v0, s2, v4
	s_add_i32 s27, s18, 0x2000
	v_and_or_b32 v5, v2, s93, v3
	v_mul_hi_i32_i24_e32 v3, 0xc00, v0
	v_mul_i32_i24_e32 v2, 0xc00, v0
	s_ashr_i32 s12, s27, 8
	v_lshl_add_u64 v[2:3], s[60:61], 0, v[2:3]
	v_lshlrev_b32_e32 v0, 1, v5
	s_and_b32 s2, s12, -16
	s_lshr_b32 s12, s12, 1
	v_lshl_add_u64 v[2:3], v[2:3], 0, v[0:1]
	s_add_i32 s19, s18, 0x100
	s_and_b32 s38, s12, 4
	v_lshl_add_u64 v[2:3], v[2:3], 0, s[96:97]
	s_mov_b32 m0, s19
	s_or_b32 s12, s38, s2
	global_load_lds_dwordx4 v[2:3], off
	v_or_b32_e32 v2, s12, v4
	v_mul_hi_i32_i24_e32 v3, 0xc00, v2
	v_mul_i32_i24_e32 v2, 0xc00, v2
	v_lshl_add_u64 v[2:3], s[60:61], 0, v[2:3]
	v_lshl_add_u64 v[2:3], v[2:3], 0, v[0:1]
	v_lshl_add_u64 v[2:3], v[2:3], 0, s[96:97]
	s_add_i32 m0, s19, 0x2000
	v_mov_b32_e32 v0, v230
	global_load_lds_dwordx4 v[2:3], off
	s_nop 0
	v_lshlrev_b32_e32 v0, 4, v0
	v_and_b32_e32 v7, 0x3f0, v0
	v_or_b32_e32 v0, s18, v7
	v_mul_hi_i32 v2, v0, s79
	v_lshrrev_b32_e32 v3, 31, v2
	v_ashrrev_i32_e32 v2, 6, v2
	v_add_u32_e32 v4, v2, v3
	v_mul_i32_i24_e32 v2, 0x180, v4
	v_sub_u32_e32 v0, v0, v2
	v_lshrrev_b32_e32 v3, 2, v4
	v_ashrrev_i32_e32 v0, 4, v0
	v_bfe_u32 v2, v4, 1, 2
	v_and_b32_e32 v3, 4, v3
	v_bitop3_b32 v0, v2, v0, v3 bitop3:0x36
	v_cmp_gt_i32_e32 vcc, 8, v0
	v_lshlrev_b32_e32 v0, 3, v0
	s_and_saveexec_b64 s[12:13], vcc
	s_xor_b64 s[12:13], exec, s[12:13]
	v_mul_hi_i32_i24_e32 v3, 0x2600, v4
	v_mul_i32_i24_e32 v2, 0x2600, v4
	v_lshl_add_u64 v[2:3], s[72:73], 0, v[2:3]
	v_ashrrev_i32_e32 v5, 31, v0
	v_mov_b32_e32 v4, v0
	v_lshl_add_u64 v[2:3], v[4:5], 1, v[2:3]
	s_andn2_saveexec_b64 s[12:13], s[12:13]
	v_mul_hi_i32_i24_e32 v3, 0xc00, v4
	v_mul_i32_i24_e32 v2, 0xc00, v4
	v_lshl_add_u64 v[2:3], s[60:61], 0, v[2:3]
	s_movk_i32 s34, 0xff80
	v_lshl_add_u64 v[2:3], v[0:1], 1, v[2:3]
	s_mov_b32 s35, -1
	v_lshl_add_u64 v[2:3], v[2:3], 0, s[34:35]
	s_or_b64 exec, exec, s[12:13]
	s_add_i32 m0, s19, 0xc000
	s_nop 0
	global_load_lds_dwordx4 v[2:3], off
	v_or_b32_e32 v2, s27, v7
	v_mul_hi_i32 v0, v2, s79
	v_lshrrev_b32_e32 v3, 31, v0
	v_ashrrev_i32_e32 v0, 6, v0
	v_add_u32_e32 v0, v0, v3
	v_mul_i32_i24_e32 v3, 0x180, v0
	v_sub_u32_e32 v2, v2, v3
	v_lshrrev_b32_e32 v4, 2, v0
	v_ashrrev_i32_e32 v2, 4, v2
	v_bfe_u32 v3, v0, 1, 2
	v_and_b32_e32 v4, 4, v4
	v_bitop3_b32 v2, v3, v2, v4 bitop3:0x36
	v_cmp_gt_i32_e32 vcc, 8, v2
	v_lshlrev_b32_e32 v2, 3, v2
	s_and_saveexec_b64 s[12:13], vcc
	s_xor_b64 s[12:13], exec, s[12:13]
; #define LAS __attribute__((address_space(3)))
; template <int MODE, int VARI>
; __device__ __forceinline__ void attn_unit(LAS unsigned char* lds, const int tid, const AttnP& a, float c2, float lam, const float* subln, float outscale, float fox_u, const bool fast) {
;     ...
;     const unsigned krb = (unsigned)(uintptr_t)K_lds + r32 * (KW * 2), kxm = kswz<KW>(r32), kcb = kcoff * 2 + hi * 16;
;     const unsigned vb0 = (unsigned)(uintptr_t)V_lds + v_rd_base(lane);
;     float m_reg = -1e30f, l_reg = 0.f; f32x16 o[4];
; #pragma unroll
;     for (int d = 0; d < 4; ++d)
; #pragma unroll
;         for (int r = 0; r < 16; ++r) o[d][r] = 0.f;
;     ...
;       unsigned voff[2], koff[KW / 64], kstp[KW / 64], boff = 0; int vt = t_lo, kt = t_lo;
;       { int tt_ = tid; asm volatile("" : "+v"(tt_)); const int ln_ = tt_ & 63;
; #pragma unroll
;         for (int i_ = 0; i_ < 2; ++i_) { const int ch_ = wid + 8 * i_, b_ = ch_ * 1024 + ln_ * 16, sub_ = b_ >> 9, wi_ = (b_ & 511) >> 1;
;             const int kk_ = (sub_ >> 2) * 8 + (wi_ >> 5), c_ = (sub_ & 3) * 32 + (wi_ & 31), k_ = (kk_ & ~0xC) | ((kk_ & 4) << 1) | ((kk_ & 8) >> 1);
;             voff[i_] = (unsigned)(((t_lo * 64 + k_) * a.vpitch + c_) * 2); }
; #pragma unroll
;         for (int i_ = 0; i_ < KW / 64; ++i_) { const int ch_ = wid + 8 * i_, b_ = ch_ * 1024 + ln_ * 16, krow_ = b_ / (KW * 2), cs_ = (b_ % (KW * 2)) >> 4;
;             const int kcc_ = cs_ ^ (kswz<KW>(krow_) >> 4);
;             if (MODE == 2 && kcc_ >= 8) { koff[i_] = (unsigned)((const char*)a.K1 - (const char*)a.K0) + (unsigned)(((t_lo * 64 + krow_) * a.k1pitch + (kcc_ - 8) * 8) * 2); kstp[i_] = (unsigned)(64 * a.k1pitch * 2); }
;             else { koff[i_] = (unsigned)(((t_lo * 64 + krow_) * a.k0pitch + kcc_ * 8) * 2); kstp[i_] = (unsigned)(64 * a.k0pitch * 2); } }
;         if (MODE == 1) boff = (unsigned)((t_lo * 64 + ln_) * 32); }
;     ...
;       LAS float* Bw_lds = B_lds + wid * 192;
;       const float ctp = ct2 + cP0;
;       int i0 = t_lo % 3, i1 = (t_lo + 1) % 3, i2 = (t_lo + 2) % 3;
;       DMA_K(t_lo, i0); DMA_V(t_lo, i0); DMA_K(t_lo + 1, i1); DMA_V(t_lo + 1, i1); DMA_K(t_lo + 2, i2);
;       asm volatile("s_waitcnt vmcnt(0)" ::: "memory"); __builtin_amdgcn_s_barrier(); asm volatile("" ::: "memory");
	v_mul_hi_i32_i24_e32 v5, 0x2600, v0
	v_mul_i32_i24_e32 v4, 0x2600, v0
	v_lshl_add_u64 v[4:5], s[72:73], 0, v[4:5]
	v_ashrrev_i32_e32 v3, 31, v2
	v_lshl_add_u64 v[4:5], v[2:3], 1, v[4:5]
	s_andn2_saveexec_b64 s[12:13], s[12:13]
	v_mul_hi_i32_i24_e32 v5, 0xc00, v0
	v_mul_i32_i24_e32 v4, 0xc00, v0
	v_lshl_add_u64 v[4:5], s[60:61], 0, v[4:5]
	v_mov_b32_e32 v3, v1
	s_movk_i32 s34, 0xff80
	v_lshl_add_u64 v[2:3], v[2:3], 1, v[4:5]
	s_mov_b32 s35, -1
	v_lshl_add_u64 v[4:5], v[2:3], 0, s[34:35]
	s_or_b64 exec, exec, s[12:13]
	s_add_i32 m0, s19, 0xe000
	s_add_i32 s36, s18, 0x4000
	global_load_lds_dwordx4 v[4:5], off
	v_or_b32_e32 v2, s36, v7
	v_mul_hi_i32 v0, v2, s79
	v_lshrrev_b32_e32 v3, 31, v0
	v_ashrrev_i32_e32 v0, 6, v0
	v_add_u32_e32 v0, v0, v3
	v_mul_i32_i24_e32 v3, 0x180, v0
	v_sub_u32_e32 v2, v2, v3
	v_lshrrev_b32_e32 v4, 2, v0
	v_ashrrev_i32_e32 v2, 4, v2
	v_bfe_u32 v3, v0, 1, 2
	v_and_b32_e32 v4, 4, v4
	v_bitop3_b32 v2, v3, v2, v4 bitop3:0x36
	v_cmp_gt_i32_e32 vcc, 8, v2
	v_lshlrev_b32_e32 v4, 3, v2
	s_and_saveexec_b64 s[12:13], vcc
	s_xor_b64 s[12:13], exec, s[12:13]
	v_mul_hi_i32_i24_e32 v3, 0x2600, v0
	v_mul_i32_i24_e32 v2, 0x2600, v0
	v_lshl_add_u64 v[2:3], s[72:73], 0, v[2:3]
	v_ashrrev_i32_e32 v5, 31, v4
	v_lshl_add_u64 v[2:3], v[4:5], 1, v[2:3]
	s_andn2_saveexec_b64 s[12:13], s[12:13]
	v_mul_hi_i32_i24_e32 v3, 0xc00, v0
	v_mul_i32_i24_e32 v2, 0xc00, v0
	v_lshl_add_u64 v[2:3], s[60:61], 0, v[2:3]
	v_mov_b32_e32 v5, v1
	s_movk_i32 s34, 0xff80
	v_lshl_add_u64 v[2:3], v[4:5], 1, v[2:3]
	s_mov_b32 s35, -1
	v_lshl_add_u64 v[2:3], v[2:3], 0, s[34:35]
	s_or_b64 exec, exec, s[12:13]
	s_add_i32 s12, s78, 0x100
	s_add_i32 m0, s12, s36
	v_lshrrev_b32_e32 v4, 2, v6
	global_load_lds_dwordx4 v[2:3], off
	v_ashrrev_i32_e32 v2, 5, v6
	v_lshrrev_b32_e32 v3, 1, v6
	v_and_b32_e32 v4, 4, v4
	v_and_b32_e32 v0, 31, v6
	v_and_or_b32 v3, v3, 3, v4
	v_lshlrev_b32_e32 v112, 4, v2
	v_mov_b32_e32 v7, s12
	s_movk_i32 s12, 0x180
	v_lshlrev_b32_e32 v4, 4, v6
	v_lshlrev_b32_e32 v5, 1, v6
	v_lshlrev_b32_e32 v3, 4, v3
	v_mad_u32_u24 v113, v0, s12, v7
	v_lshlrev_b32_e32 v7, 3, v6
	v_cmp_gt_u32_e64 s[12:13], 32, v6
	v_add_u32_e32 v6, 32, v112
	v_xor_b32_e32 v116, v3, v6
	v_add_u32_e32 v6, 64, v112
	v_xor_b32_e32 v117, v3, v6
	v_add_u32_e32 v6, 0x60, v112
	v_xor_b32_e32 v118, v3, v6
	v_add_u32_e32 v6, 0x80, v112
	v_xor_b32_e32 v119, v3, v6
	v_add_u32_e32 v6, 0xa0, v112
	v_xor_b32_e32 v120, v3, v6
	v_add_u32_e32 v6, 0xc0, v112
	v_xor_b32_e32 v121, v3, v6
	v_add_u32_e32 v6, 0xe0, v112
	v_xor_b32_e32 v122, v3, v6
	v_add_u32_e32 v6, 0x100, v112
	v_xor_b32_e32 v123, v3, v6
	v_add_u32_e32 v6, 0x120, v112
	v_xor_b32_e32 v124, v3, v6
	v_add_u32_e32 v6, 0x140, v112
	v_and_b32_e32 v5, 32, v5
	v_xor_b32_e32 v125, v3, v6
	v_add_u32_e32 v6, 0x160, v112
	s_movk_i32 s33, 0x118
	v_and_b32_e32 v4, 0xc0, v4
	v_lshlrev_b32_e32 v2, 2, v2
	v_lshl_add_u32 v114, v0, 2, s26
	v_xor_b32_e32 v115, v3, v112
	v_xor_b32_e32 v126, v3, v6
	v_and_or_b32 v3, v7, s33, v5
	s_movk_i32 s33, 0x100
	v_add_u32_e32 v0, s6, v0
	v_mov_b32_e32 v14, v1
	v_mov_b32_e32 v15, v1
	v_add3_u32 v127, v4, s33, v3
	v_sub_u32_e32 v128, v0, v2
	s_add_i32 s35, s14, s15
	s_add_i32 s38, s2, s38
	v_mov_b32_e32 v0, v1
	v_mov_b32_e32 v2, v1
	v_mov_b32_e32 v3, v1
	v_mov_b32_e32 v4, v1
	v_mov_b32_e32 v5, v1
	v_mov_b32_e32 v6, v1
	v_mov_b32_e32 v7, v1
	v_mov_b32_e32 v8, v1
	v_mov_b32_e32 v9, v1
	v_mov_b32_e32 v10, v1
	v_mov_b32_e32 v11, v1
	v_mov_b32_e32 v12, v1
	v_mov_b32_e32 v13, v1
	v_mov_b64_e32 v[30:31], v[14:15]
	v_mov_b64_e32 v[46:47], v[14:15]
	v_mov_b64_e32 v[62:63], v[14:15]
	v_mov_b64_e32 v[78:79], v[14:15]
	s_mov_b32 s34, 1
	s_add_i32 s35, s35, 64
	s_add_i32 s38, s38, 64
	s_mov_b32 s39, 0
	v_mov_b32_e32 v130, 0
	v_mov_b32_e32 v129, 0xf149f2ca
	v_mov_b64_e32 v[28:29], v[12:13]
	v_mov_b64_e32 v[26:27], v[10:11]
	v_mov_b64_e32 v[24:25], v[8:9]
	v_mov_b64_e32 v[22:23], v[6:7]
	v_mov_b64_e32 v[20:21], v[4:5]
	v_mov_b64_e32 v[18:19], v[2:3]
	v_mov_b64_e32 v[16:17], v[0:1]
	v_mov_b64_e32 v[44:45], v[12:13]
	v_mov_b64_e32 v[42:43], v[10:11]
	v_mov_b64_e32 v[40:41], v[8:9]
	v_mov_b64_e32 v[38:39], v[6:7]
	v_mov_b64_e32 v[36:37], v[4:5]
	v_mov_b64_e32 v[34:35], v[2:3]
	v_mov_b64_e32 v[32:33], v[0:1]
	v_mov_b64_e32 v[60:61], v[12:13]
	v_mov_b64_e32 v[58:59], v[10:11]
	v_mov_b64_e32 v[56:57], v[8:9]
	v_mov_b64_e32 v[54:55], v[6:7]
	v_mov_b64_e32 v[52:53], v[4:5]
	v_mov_b64_e32 v[50:51], v[2:3]
	v_mov_b64_e32 v[48:49], v[0:1]
	v_mov_b64_e32 v[76:77], v[12:13]
	v_mov_b64_e32 v[74:75], v[10:11]
	v_mov_b64_e32 v[72:73], v[8:9]
	v_mov_b64_e32 v[70:71], v[6:7]
	v_mov_b64_e32 v[68:69], v[4:5]
	v_mov_b64_e32 v[66:67], v[2:3]
	v_mov_b64_e32 v[64:65], v[0:1]
	s_waitcnt vmcnt(0) lgkmcnt(0)
	s_barrier
	s_add_i32 s2, s34, -1
	s_and_b32 s40, s2, 1
	s_cmp_ge_u32 s34, s59
	s_cbranch_scc1 .LBB0_600

; #define LAS __attribute__((address_space(3)))
; __global__ void __launch_bounds__(512, 2) fwd_kernel(Args a_unused) {
;     extern __shared__ __attribute__((aligned(16))) unsigned char lds_raw[];
;     LAS unsigned char* lds = (LAS unsigned char*)lds_raw;
;     cg::grid_group grid = cg::this_grid();
;     ArgsP a0 = (ArgsP)__builtin_amdgcn_kernarg_segment_ptr();
;     const int G = gridDim.x, ph_lo = a0->ph_lo, ph_hi = a0->ph_hi;
;     volatile LAS unsigned* bst = (volatile LAS unsigned*)(lds + 131072 + 128);
;     if (threadIdx.x == 0) { bst[0] = 0u; bst[1] = 0u; }
;     __syncthreads();
;     (void)xcd_barrier_post((unsigned*)(a0->ws + WS_BAR), bst);
	.amdhsa_kernel _Z10fwd_kernel4Args
		.amdhsa_group_segment_fixed_size 256
		.amdhsa_private_segment_fixed_size 0
		.amdhsa_kernarg_size 464
		.amdhsa_user_sgpr_count 2
		.amdhsa_user_sgpr_dispatch_ptr 0
		.amdhsa_user_sgpr_queue_ptr 0
		.amdhsa_user_sgpr_kernarg_segment_ptr 1
		.amdhsa_user_sgpr_dispatch_id 0
		.amdhsa_user_sgpr_kernarg_preload_length 0
		.amdhsa_user_sgpr_kernarg_preload_offset 0
		.amdhsa_user_sgpr_private_segment_size 0
		.amdhsa_uses_dynamic_stack 0
		.amdhsa_enable_private_segment 0
		.amdhsa_system_sgpr_workgroup_id_x 1
		.amdhsa_system_sgpr_workgroup_id_y 0
		.amdhsa_system_sgpr_workgroup_id_z 0
		.amdhsa_system_sgpr_workgroup_info 0
		.amdhsa_system_vgpr_workitem_id 2
		.amdhsa_next_free_vgpr 256
		.amdhsa_next_free_sgpr 102
		.amdhsa_accum_offset 256
		.amdhsa_reserve_vcc 1
		.amdhsa_float_round_mode_32 0
		.amdhsa_float_round_mode_16_64 0
		.amdhsa_float_denorm_mode_32 3
		.amdhsa_float_denorm_mode_16_64 3
		.amdhsa_dx10_clamp 1
		.amdhsa_ieee_mode 1
		.amdhsa_fp16_overflow 0
		.amdhsa_tg_split 0
		.amdhsa_exception_fp_ieee_invalid_op 0
		.amdhsa_exception_fp_denorm_src 0
		.amdhsa_exception_fp_ieee_div_zero 0
		.amdhsa_exception_fp_ieee_overflow 0
		.amdhsa_exception_fp_ieee_underflow 0
		.amdhsa_exception_fp_ieee_inexact 0
		.amdhsa_exception_int_div_zero 0
	.end_amdhsa_kernel

; #define LAS __attribute__((address_space(3)))
; __global__ void __launch_bounds__(512, 2) fwd_kernel(Args a_unused) {
;     extern __shared__ __attribute__((aligned(16))) unsigned char lds_raw[];
;     LAS unsigned char* lds = (LAS unsigned char*)lds_raw;
;     cg::grid_group grid = cg::this_grid();
;     ArgsP a0 = (ArgsP)__builtin_amdgcn_kernarg_segment_ptr();
;     const int G = gridDim.x, ph_lo = a0->ph_lo, ph_hi = a0->ph_hi;
amdhsa.kernels:
  - .agpr_count:     0
    .args:
      - .offset:         0
        .size:           208
        .value_kind:     by_value
      - .offset:         208
        .size:           4
        .value_kind:     hidden_block_count_x
      - .offset:         212
        .size:           4
        .value_kind:     hidden_block_count_y
      - .offset:         216
        .size:           4
        .value_kind:     hidden_block_count_z
      - .offset:         220
        .size:           2
        .value_kind:     hidden_group_size_x
      - .offset:         222
        .size:           2
        .value_kind:     hidden_group_size_y
      - .offset:         224
        .size:           2
        .value_kind:     hidden_group_size_z
      - .offset:         226
        .size:           2
        .value_kind:     hidden_remainder_x
      - .offset:         228
        .size:           2
        .value_kind:     hidden_remainder_y
      - .offset:         230
        .size:           2
        .value_kind:     hidden_remainder_z
      - .offset:         248
        .size:           8
        .value_kind:     hidden_global_offset_x
      - .offset:         256
        .size:           8
        .value_kind:     hidden_global_offset_y
      - .offset:         264
        .size:           8
        .value_kind:     hidden_global_offset_z
      - .offset:         272
        .size:           2
        .value_kind:     hidden_grid_dims
      - .offset:         296
        .size:           8
        .value_kind:     hidden_multigrid_sync_arg
      - .offset:         328
        .size:           4
        .value_kind:     hidden_dynamic_lds_size
    .group_segment_fixed_size: 256
    .kernarg_segment_align: 8
    .kernarg_segment_size: 464
    .language:       OpenCL C
    .language_version:
      - 2
      - 0
    .max_flat_workgroup_size: 512
    .name:           _Z10fwd_kernel4Args
    .private_segment_fixed_size: 0
    .sgpr_count:     108
    .sgpr_spill_count: 110
    .symbol:         _Z10fwd_kernel4Args.kd
    .uniform_work_group_size: 1
    .uses_dynamic_stack: false
    .vgpr_count:     256
    .vgpr_spill_count: 0
    .wavefront_size: 64
